# GLA top-of-chunk wait relaxed from vmcnt(6) to vmcnt(22): only the k tile loads are waited, not the earlier q~/O stores
# speedup vs baseline: 1.0117x; 1.0100x over previous
; #define LAS __attribute__((address_space(3)))
; template <bool PASS2>
; __device__ __forceinline__ void gla_pass(LAS unsigned char* lds, const Params& p, int layer) {
;     ...
;             GLA_ISSUE(0);
; #pragma unroll 1
;             for (int cc = 0; cc < 8; ++cc) {
;                 const int chunk = dir ? 7 - cc : cc;
;                 const int t0 = b * SEQL + grp * 512 + chunk * 64;
; #pragma unroll
;                 for (int it = 0; it < 2; ++it) { const int pi = tid + 512 * it, row = pi >> 4, seg = pi & 15;
;                     *(LAS u32x4*)(lds + SK + row * 272 + seg * 16) = rk[it];
;                     if (PASS2) rq[it] = *(const u32x4*)(P + (size_t)(t0 + row) * PW + h * 128 + seg * 8); }
; #pragma unroll
;                 for (int it = 0; it < 4; ++it) { const int pi = tid + 512 * it, row = pi >> 5, seg = pi & 31;
;                     rv[it] = *(const u32x4*)(P + (size_t)(t0 + row) * PW + 1024 + h * 256 + seg * 8); }
;                 if (tid < 256) { const int row = tid >> 2, seg = tid & 3; *(LAS u32x4*)(lds + SLR + row * 64 + seg * 16) = rl; }
.LBB0_453:
	s_sub_i32 s66, 7, s68
	s_and_b64 s[4:5], s[14:15], exec
	s_cselect_b32 s4, s68, s66
	s_lshl_b32 s69, s4, 6
	s_add_i32 s69, s69, s97
	v_add_u32_e32 v108, v184, v191
	s_waitcnt vmcnt(22)
	ds_write_b128 v108, v[0:3] offset:17408
	v_add_u32_e32 v108, v184, v192
	s_waitcnt vmcnt(22)
	ds_write_b128 v108, v[4:7] offset:17408
	s_sub_i32 s66, 6, s68
	s_add_i32 s4, s68, 1
	s_and_b64 vcc, s[14:15], exec
	s_cselect_b32 s4, s4, s66
	s_lshl_b32 s66, s4, 6
	s_add_i32 s66, s66, s97
	v_add_u32_e32 v0, s66, v189
	v_add_u32_e32 v2, s66, v190
	v_mad_i64_i32 v[0:1], s[4:5], v0, s80, v[140:141]
	v_mad_i64_i32 v[4:5], s[4:5], v2, s80, v[140:141]
	global_load_dwordx4 v[0:3], v[0:1], off offset:1024
	s_nop 0
	global_load_dwordx4 v[4:7], v[4:5], off offset:1024
	s_and_saveexec_b64 s[4:5], s[12:13]
	s_cbranch_execz .Lgla_t3_skip
	v_add_u32_e32 v8, s66, v188
	v_ashrrev_i32_e32 v9, 31, v8
	v_lshlrev_b64 v[8:9], 7, v[8:9]
	v_lshl_add_u64 v[8:9], v[164:165], 0, v[8:9]
	global_load_dwordx4 v[8:11], v[8:9], off
